# attention steady loop rewritten by hand: K/V LDS fragment prefetch with counted lgkmcnt, SGPR-based LDS-DMA addressing, balanced max tree, 2x unrolled over LDS stages
# speedup vs baseline: 1.0551x; 1.0551x over previous
.LBB0_1480:
	v_readfirstlane_b32 s44, v203
	v_readfirstlane_b32 s45, v205
	s_mov_b64 s[40:41], s[94:95]
	s_mov_b64 s[42:43], s[94:95]
	s_movk_i32 s46, 0x41
	s_add_u32 s45, s45, 0x2000
.Latt_loop:
	s_waitcnt vmcnt(0)
	s_barrier
	ds_read_b128 v[64:67], v173 offset:24576
	ds_read_b128 v[68:71], v173 offset:28672
	s_mov_b32 m0, s44
	ds_read_b128 v[72:75], v171 offset:24576
	global_load_lds_dwordx4 v200, s[40:41]
	s_add_u32 m0, s44, 0x400
	ds_read_b128 v[76:79], v171 offset:28672
	global_load_lds_dwordx4 v190, s[40:41]
	s_mov_b32 m0, s45
	ds_read_b128 v[216:219], v169 offset:24576
	global_load_lds_dwordx4 v192, s[42:43]
	s_add_u32 m0, s45, 0x400
	ds_read_b128 v[220:223], v169 offset:28672
	global_load_lds_dwordx4 v194, s[42:43]
	s_add_u32 m0, s45, 0x800
	ds_read_b128 v[224:227], v167 offset:24576
	global_load_lds_dwordx4 v196, s[42:43]
	s_add_u32 m0, s45, 0xc00
	ds_read_b128 v[228:231], v167 offset:28672
	global_load_lds_dwordx4 v198, s[42:43]
	ds_read_b128 v[232:235], v173 offset:32768
	ds_read_b128 v[236:239], v173 offset:36864
	ds_read_b128 v[240:243], v173 offset:40960
	ds_read_b128 v[244:247], v173 offset:45056
	s_add_u32 s40, s40, 0x18000
	s_addc_u32 s41, s41, 0
	s_add_u32 s42, s42, 0x80
	s_addc_u32 s43, s43, 0
	s_waitcnt lgkmcnt(11)
	v_mfma_f32_32x32x16_bf16 v[112:127], v[64:67], v[140:143], v[96:111]
	ds_read_b128 v[64:67], v171 offset:32768
	s_waitcnt lgkmcnt(11)
	v_mfma_f32_32x32x16_bf16 v[80:95], v[68:71], v[140:143], v[96:111]
	ds_read_b128 v[68:71], v171 offset:36864
	s_waitcnt lgkmcnt(11)
	v_mfma_f32_32x32x16_bf16 v[112:127], v[72:75], v[136:139], v[112:127]
	ds_read_b128 v[72:75], v171 offset:40960
	s_waitcnt lgkmcnt(11)
	v_mfma_f32_32x32x16_bf16 v[80:95], v[76:79], v[136:139], v[80:95]
	ds_read_b128 v[76:79], v171 offset:45056
	s_waitcnt lgkmcnt(11)
	v_mfma_f32_32x32x16_bf16 v[112:127], v[216:219], v[132:135], v[112:127]
	ds_read_b128 v[216:219], v169 offset:32768
	s_waitcnt lgkmcnt(11)
	v_mfma_f32_32x32x16_bf16 v[80:95], v[220:223], v[132:135], v[80:95]
	ds_read_b128 v[220:223], v169 offset:36864
	s_waitcnt lgkmcnt(11)
	v_mfma_f32_32x32x16_bf16 v[112:127], v[224:227], v[128:131], v[112:127]
	ds_read_b128 v[224:227], v169 offset:40960
	s_waitcnt lgkmcnt(11)
	v_mfma_f32_32x32x16_bf16 v[80:95], v[228:231], v[128:131], v[80:95]
	ds_read_b128 v[228:231], v169 offset:45056
	s_nop 7
	s_nop 3
	v_max3_f32 v175, v112, v113, v114
	v_max3_f32 v177, v115, v116, v117
	v_max3_f32 v179, v118, v119, v120
	v_max3_f32 v181, v121, v122, v123
	v_max3_f32 v248, v124, v125, v126
	v_max3_f32 v249, v127, v80, v81
	v_max3_f32 v250, v82, v83, v84
	v_max3_f32 v251, v85, v86, v87
	v_max3_f32 v253, v88, v89, v90
	v_max3_f32 v254, v91, v92, v93
	v_max_f32_e32 v255, v94, v95
	v_max3_f32 v175, v175, v177, v179
	v_max3_f32 v181, v181, v248, v249
	v_max3_f32 v250, v250, v251, v253
	v_max_f32_e32 v254, v254, v255
	v_max3_f32 v175, v175, v181, v250
	v_max_f32_e32 v175, v175, v254
	v_mov_b32_e32 v177, v175
	s_nop 1
	v_permlane32_swap_b32_e32 v175, v177
	v_max_f32_e32 v175, v175, v177
	v_cmp_lt_f32_e32 vcc, 0, v175
	s_cbranch_vccnz .Latt_resc_a
.Latt_cont_a:
	v_exp_f32_e32 v112, v112
	v_exp_f32_e32 v113, v113
	v_exp_f32_e32 v114, v114
	v_exp_f32_e32 v115, v115
	v_exp_f32_e32 v116, v116
	v_exp_f32_e32 v117, v117
	v_exp_f32_e32 v118, v118
	v_exp_f32_e32 v119, v119
	v_add_f32_e32 v183, v112, v113
	v_add_f32_e32 v183, v183, v114
	v_add_f32_e32 v183, v183, v115
	v_add_f32_e32 v183, v183, v116
	v_add_f32_e32 v183, v183, v117
	v_add_f32_e32 v183, v183, v118
	v_add_f32_e32 v183, v183, v119
	v_cvt_pk_bf16_f32 v112, v112, v113
	v_cvt_pk_bf16_f32 v113, v114, v115
	v_cvt_pk_bf16_f32 v114, v116, v117
	v_cvt_pk_bf16_f32 v115, v118, v119
	v_exp_f32_e32 v120, v120
	v_exp_f32_e32 v121, v121
	s_waitcnt lgkmcnt(8)
	v_mfma_f32_32x32x16_bf16 v[48:63], v[232:235], v[112:115], v[48:63]
	v_exp_f32_e32 v122, v122
	v_exp_f32_e32 v123, v123
	v_exp_f32_e32 v124, v124
	v_mfma_f32_32x32x16_bf16 v[32:47], v[236:239], v[112:115], v[32:47]
	v_exp_f32_e32 v125, v125
	v_exp_f32_e32 v126, v126
	v_exp_f32_e32 v127, v127
	v_mfma_f32_32x32x16_bf16 v[16:31], v[240:243], v[112:115], v[16:31]
	v_add_f32_e32 v185, v120, v121
	v_add_f32_e32 v185, v185, v122
	v_add_f32_e32 v185, v185, v123
	v_add_f32_e32 v185, v185, v124
	v_add_f32_e32 v185, v185, v125
	v_add_f32_e32 v185, v185, v126
	v_mfma_f32_32x32x16_bf16 v[0:15], v[244:247], v[112:115], v[0:15]
	ds_read_b128 v[232:235], v167 offset:32768
	ds_read_b128 v[236:239], v167 offset:36864
	ds_read_b128 v[240:243], v167 offset:40960
	ds_read_b128 v[244:247], v167 offset:45056
	v_add_f32_e32 v185, v185, v127
	v_cvt_pk_bf16_f32 v116, v120, v121
	v_cvt_pk_bf16_f32 v117, v122, v123
	v_cvt_pk_bf16_f32 v118, v124, v125
	v_cvt_pk_bf16_f32 v119, v126, v127
	s_nop 0
	s_waitcnt lgkmcnt(8)
	v_mfma_f32_32x32x16_bf16 v[48:63], v[64:67], v[116:119], v[48:63]
	v_exp_f32_e32 v80, v80
	v_exp_f32_e32 v81, v81
	v_exp_f32_e32 v82, v82
	v_mfma_f32_32x32x16_bf16 v[32:47], v[68:71], v[116:119], v[32:47]
	v_exp_f32_e32 v83, v83
	v_exp_f32_e32 v84, v84
	v_exp_f32_e32 v85, v85
	v_mfma_f32_32x32x16_bf16 v[16:31], v[72:75], v[116:119], v[16:31]
	v_exp_f32_e32 v86, v86
	v_exp_f32_e32 v87, v87
	v_add_f32_e32 v187, v80, v81
	v_add_f32_e32 v187, v187, v82
	v_mfma_f32_32x32x16_bf16 v[0:15], v[76:79], v[116:119], v[0:15]
	v_add_f32_e32 v187, v187, v83
	v_add_f32_e32 v187, v187, v84
	v_add_f32_e32 v187, v187, v85
	v_add_f32_e32 v187, v187, v86
	v_add_f32_e32 v187, v187, v87
	v_cvt_pk_bf16_f32 v80, v80, v81
	v_cvt_pk_bf16_f32 v81, v82, v83
	v_cvt_pk_bf16_f32 v82, v84, v85
	v_cvt_pk_bf16_f32 v83, v86, v87
	s_nop 0
	s_waitcnt lgkmcnt(4)
	v_mfma_f32_32x32x16_bf16 v[48:63], v[216:219], v[80:83], v[48:63]
	v_exp_f32_e32 v88, v88
	v_exp_f32_e32 v89, v89
	v_exp_f32_e32 v90, v90
	v_mfma_f32_32x32x16_bf16 v[32:47], v[220:223], v[80:83], v[32:47]
	v_exp_f32_e32 v91, v91
	v_exp_f32_e32 v92, v92
	v_exp_f32_e32 v93, v93
	v_mfma_f32_32x32x16_bf16 v[16:31], v[224:227], v[80:83], v[16:31]
	v_exp_f32_e32 v94, v94
	v_exp_f32_e32 v95, v95
	v_add_f32_e32 v215, v88, v89
	v_add_f32_e32 v215, v215, v90
	v_mfma_f32_32x32x16_bf16 v[0:15], v[228:231], v[80:83], v[0:15]
	v_add_f32_e32 v215, v215, v91
	v_add_f32_e32 v215, v215, v92
	v_add_f32_e32 v215, v215, v93
	v_add_f32_e32 v215, v215, v94
	v_add_f32_e32 v215, v215, v95
	v_cvt_pk_bf16_f32 v84, v88, v89
	v_cvt_pk_bf16_f32 v85, v90, v91
	v_cvt_pk_bf16_f32 v86, v92, v93
	v_cvt_pk_bf16_f32 v87, v94, v95
	s_nop 0
	s_waitcnt lgkmcnt(0)
	v_mfma_f32_32x32x16_bf16 v[48:63], v[232:235], v[84:87], v[48:63]
	v_add_f32_e32 v183, v183, v185
	v_add_f32_e32 v187, v187, v215
	v_add_f32_e32 v183, v183, v187
	v_mov_b32_e32 v185, v183
	v_mfma_f32_32x32x16_bf16 v[32:47], v[236:239], v[84:87], v[32:47]
	v_mfma_f32_32x32x16_bf16 v[16:31], v[240:243], v[84:87], v[16:31]
	v_mfma_f32_32x32x16_bf16 v[0:15], v[244:247], v[84:87], v[0:15]
	s_nop 0
	s_nop 0
	v_permlane32_swap_b32_e32 v183, v185
	v_add_f32_e32 v183, v183, v185
	v_add_f32_e32 v189, v189, v183
	s_waitcnt vmcnt(0)
	s_barrier
	ds_read_b128 v[64:67], v173 offset:0
	ds_read_b128 v[68:71], v173 offset:4096
	s_add_u32 m0, s44, 0x6000
	ds_read_b128 v[72:75], v171 offset:0
	global_load_lds_dwordx4 v200, s[40:41]
	s_add_u32 m0, s44, 0x6400
	ds_read_b128 v[76:79], v171 offset:4096
	global_load_lds_dwordx4 v190, s[40:41]
	s_add_u32 m0, s45, 0x6000
	ds_read_b128 v[216:219], v169 offset:0
	global_load_lds_dwordx4 v192, s[42:43]
	s_add_u32 m0, s45, 0x6400
	ds_read_b128 v[220:223], v169 offset:4096
	global_load_lds_dwordx4 v194, s[42:43]
	s_add_u32 m0, s45, 0x6800
	ds_read_b128 v[224:227], v167 offset:0
	global_load_lds_dwordx4 v196, s[42:43]
	s_add_u32 m0, s45, 0x6c00
	ds_read_b128 v[228:231], v167 offset:4096
	global_load_lds_dwordx4 v198, s[42:43]
	ds_read_b128 v[232:235], v173 offset:8192
	ds_read_b128 v[236:239], v173 offset:12288
	ds_read_b128 v[240:243], v173 offset:16384
	ds_read_b128 v[244:247], v173 offset:20480
	s_add_u32 s40, s40, 0x18000
	s_addc_u32 s41, s41, 0
	s_add_u32 s42, s42, 0x80
	s_addc_u32 s43, s43, 0
	s_waitcnt lgkmcnt(11)
	v_mfma_f32_32x32x16_bf16 v[112:127], v[64:67], v[140:143], v[96:111]
	ds_read_b128 v[64:67], v171 offset:8192
	s_waitcnt lgkmcnt(11)
	v_mfma_f32_32x32x16_bf16 v[80:95], v[68:71], v[140:143], v[96:111]
	ds_read_b128 v[68:71], v171 offset:12288
	s_waitcnt lgkmcnt(11)
	v_mfma_f32_32x32x16_bf16 v[112:127], v[72:75], v[136:139], v[112:127]
	ds_read_b128 v[72:75], v171 offset:16384
	s_waitcnt lgkmcnt(11)
	v_mfma_f32_32x32x16_bf16 v[80:95], v[76:79], v[136:139], v[80:95]
	ds_read_b128 v[76:79], v171 offset:20480
	s_waitcnt lgkmcnt(11)
	v_mfma_f32_32x32x16_bf16 v[112:127], v[216:219], v[132:135], v[112:127]
	ds_read_b128 v[216:219], v169 offset:8192
	s_waitcnt lgkmcnt(11)
	v_mfma_f32_32x32x16_bf16 v[80:95], v[220:223], v[132:135], v[80:95]
	ds_read_b128 v[220:223], v169 offset:12288
	s_waitcnt lgkmcnt(11)
	v_mfma_f32_32x32x16_bf16 v[112:127], v[224:227], v[128:131], v[112:127]
	ds_read_b128 v[224:227], v169 offset:16384
	s_waitcnt lgkmcnt(11)
	v_mfma_f32_32x32x16_bf16 v[80:95], v[228:231], v[128:131], v[80:95]
	ds_read_b128 v[228:231], v169 offset:20480
	s_nop 7
	s_nop 3
	v_max3_f32 v175, v112, v113, v114
	v_max3_f32 v177, v115, v116, v117
	v_max3_f32 v179, v118, v119, v120
	v_max3_f32 v181, v121, v122, v123
	v_max3_f32 v248, v124, v125, v126
	v_max3_f32 v249, v127, v80, v81
	v_max3_f32 v250, v82, v83, v84
	v_max3_f32 v251, v85, v86, v87
	v_max3_f32 v253, v88, v89, v90
	v_max3_f32 v254, v91, v92, v93
	v_max_f32_e32 v255, v94, v95
	v_max3_f32 v175, v175, v177, v179
	v_max3_f32 v181, v181, v248, v249
	v_max3_f32 v250, v250, v251, v253
	v_max_f32_e32 v254, v254, v255
	v_max3_f32 v175, v175, v181, v250
	v_max_f32_e32 v175, v175, v254
	v_mov_b32_e32 v177, v175
	s_nop 1
	v_permlane32_swap_b32_e32 v175, v177
	v_max_f32_e32 v175, v175, v177
	v_cmp_lt_f32_e32 vcc, 0, v175
	s_cbranch_vccnz .Latt_resc_b
.Latt_cont_b:
	v_exp_f32_e32 v112, v112
	v_exp_f32_e32 v113, v113
	v_exp_f32_e32 v114, v114
	v_exp_f32_e32 v115, v115
	v_exp_f32_e32 v116, v116
	v_exp_f32_e32 v117, v117
	v_exp_f32_e32 v118, v118
	v_exp_f32_e32 v119, v119
	v_add_f32_e32 v183, v112, v113
	v_add_f32_e32 v183, v183, v114
	v_add_f32_e32 v183, v183, v115
	v_add_f32_e32 v183, v183, v116
	v_add_f32_e32 v183, v183, v117
	v_add_f32_e32 v183, v183, v118
	v_add_f32_e32 v183, v183, v119
	v_cvt_pk_bf16_f32 v112, v112, v113
	v_cvt_pk_bf16_f32 v113, v114, v115
	v_cvt_pk_bf16_f32 v114, v116, v117
	v_cvt_pk_bf16_f32 v115, v118, v119
	v_exp_f32_e32 v120, v120
	v_exp_f32_e32 v121, v121
	s_waitcnt lgkmcnt(8)
	v_mfma_f32_32x32x16_bf16 v[48:63], v[232:235], v[112:115], v[48:63]
	v_exp_f32_e32 v122, v122
	v_exp_f32_e32 v123, v123
	v_exp_f32_e32 v124, v124
	v_mfma_f32_32x32x16_bf16 v[32:47], v[236:239], v[112:115], v[32:47]
	v_exp_f32_e32 v125, v125
	v_exp_f32_e32 v126, v126
	v_exp_f32_e32 v127, v127
	v_mfma_f32_32x32x16_bf16 v[16:31], v[240:243], v[112:115], v[16:31]
	v_add_f32_e32 v185, v120, v121
	v_add_f32_e32 v185, v185, v122
	v_add_f32_e32 v185, v185, v123
	v_add_f32_e32 v185, v185, v124
	v_add_f32_e32 v185, v185, v125
	v_add_f32_e32 v185, v185, v126
	v_mfma_f32_32x32x16_bf16 v[0:15], v[244:247], v[112:115], v[0:15]
	ds_read_b128 v[232:235], v167 offset:8192
	ds_read_b128 v[236:239], v167 offset:12288
	ds_read_b128 v[240:243], v167 offset:16384
	ds_read_b128 v[244:247], v167 offset:20480
	v_add_f32_e32 v185, v185, v127
	v_cvt_pk_bf16_f32 v116, v120, v121
	v_cvt_pk_bf16_f32 v117, v122, v123
	v_cvt_pk_bf16_f32 v118, v124, v125
	v_cvt_pk_bf16_f32 v119, v126, v127
	s_nop 0
	s_waitcnt lgkmcnt(8)
	v_mfma_f32_32x32x16_bf16 v[48:63], v[64:67], v[116:119], v[48:63]
	v_exp_f32_e32 v80, v80
	v_exp_f32_e32 v81, v81
	v_exp_f32_e32 v82, v82
	v_mfma_f32_32x32x16_bf16 v[32:47], v[68:71], v[116:119], v[32:47]
	v_exp_f32_e32 v83, v83
	v_exp_f32_e32 v84, v84
	v_exp_f32_e32 v85, v85
	v_mfma_f32_32x32x16_bf16 v[16:31], v[72:75], v[116:119], v[16:31]
	v_exp_f32_e32 v86, v86
	v_exp_f32_e32 v87, v87
	v_add_f32_e32 v187, v80, v81
	v_add_f32_e32 v187, v187, v82
	v_mfma_f32_32x32x16_bf16 v[0:15], v[76:79], v[116:119], v[0:15]
	v_add_f32_e32 v187, v187, v83
	v_add_f32_e32 v187, v187, v84
	v_add_f32_e32 v187, v187, v85
	v_add_f32_e32 v187, v187, v86
	v_add_f32_e32 v187, v187, v87
	v_cvt_pk_bf16_f32 v80, v80, v81
	v_cvt_pk_bf16_f32 v81, v82, v83
	v_cvt_pk_bf16_f32 v82, v84, v85
	v_cvt_pk_bf16_f32 v83, v86, v87
	s_nop 0
	s_waitcnt lgkmcnt(4)
	v_mfma_f32_32x32x16_bf16 v[48:63], v[216:219], v[80:83], v[48:63]
	v_exp_f32_e32 v88, v88
	v_exp_f32_e32 v89, v89
	v_exp_f32_e32 v90, v90
	v_mfma_f32_32x32x16_bf16 v[32:47], v[220:223], v[80:83], v[32:47]
	v_exp_f32_e32 v91, v91
	v_exp_f32_e32 v92, v92
	v_exp_f32_e32 v93, v93
	v_mfma_f32_32x32x16_bf16 v[16:31], v[224:227], v[80:83], v[16:31]
	v_exp_f32_e32 v94, v94
	v_exp_f32_e32 v95, v95
	v_add_f32_e32 v215, v88, v89
	v_add_f32_e32 v215, v215, v90
	v_mfma_f32_32x32x16_bf16 v[0:15], v[228:231], v[80:83], v[0:15]
	v_add_f32_e32 v215, v215, v91
	v_add_f32_e32 v215, v215, v92
	v_add_f32_e32 v215, v215, v93
	v_add_f32_e32 v215, v215, v94
	v_add_f32_e32 v215, v215, v95
	v_cvt_pk_bf16_f32 v84, v88, v89
	v_cvt_pk_bf16_f32 v85, v90, v91
	v_cvt_pk_bf16_f32 v86, v92, v93
	v_cvt_pk_bf16_f32 v87, v94, v95
	s_nop 0
	s_waitcnt lgkmcnt(0)
	v_mfma_f32_32x32x16_bf16 v[48:63], v[232:235], v[84:87], v[48:63]
	v_add_f32_e32 v183, v183, v185
	v_add_f32_e32 v187, v187, v215
	v_add_f32_e32 v183, v183, v187
	v_mov_b32_e32 v185, v183
	v_mfma_f32_32x32x16_bf16 v[32:47], v[236:239], v[84:87], v[32:47]
	v_mfma_f32_32x32x16_bf16 v[16:31], v[240:243], v[84:87], v[16:31]
	v_mfma_f32_32x32x16_bf16 v[0:15], v[244:247], v[84:87], v[0:15]
	s_nop 0
	s_nop 0
	v_permlane32_swap_b32_e32 v183, v185
	v_add_f32_e32 v183, v183, v185
	v_add_f32_e32 v189, v189, v183
	s_sub_u32 s46, s46, 1
	s_cmp_lg_u32 s46, 0
	s_cbranch_scc1 .Latt_loop
	v_mov_b64_e32 v[64:65], v[96:97]
	v_mov_b64_e32 v[66:67], v[98:99]
	v_mov_b64_e32 v[68:69], v[100:101]
	v_mov_b64_e32 v[70:71], v[102:103]
	v_mov_b64_e32 v[72:73], v[104:105]
	v_mov_b64_e32 v[74:75], v[106:107]
	v_mov_b64_e32 v[76:77], v[108:109]
	v_mov_b64_e32 v[78:79], v[110:111]
	s_branch .LBB0_1482
.Latt_resc_a:
	v_max_f32_e32 v248, 0, v175
	v_exp_f32_e64 v250, -v248
	v_sub_f32_e32 v112, v112, v248
	v_sub_f32_e32 v113, v113, v248
	v_sub_f32_e32 v114, v114, v248
	v_sub_f32_e32 v115, v115, v248
	v_sub_f32_e32 v116, v116, v248
	v_sub_f32_e32 v117, v117, v248
	v_sub_f32_e32 v118, v118, v248
	v_sub_f32_e32 v119, v119, v248
	v_sub_f32_e32 v120, v120, v248
	v_sub_f32_e32 v121, v121, v248
	v_sub_f32_e32 v122, v122, v248
	v_sub_f32_e32 v123, v123, v248
	v_sub_f32_e32 v124, v124, v248
	v_sub_f32_e32 v125, v125, v248
	v_sub_f32_e32 v126, v126, v248
	v_sub_f32_e32 v127, v127, v248
	v_sub_f32_e32 v80, v80, v248
	v_sub_f32_e32 v81, v81, v248
	v_sub_f32_e32 v82, v82, v248
	v_sub_f32_e32 v83, v83, v248
	v_sub_f32_e32 v84, v84, v248
	v_sub_f32_e32 v85, v85, v248
	v_sub_f32_e32 v86, v86, v248
	v_sub_f32_e32 v87, v87, v248
	v_sub_f32_e32 v88, v88, v248
	v_sub_f32_e32 v89, v89, v248
	v_sub_f32_e32 v90, v90, v248
	v_sub_f32_e32 v91, v91, v248
	v_sub_f32_e32 v92, v92, v248
	v_sub_f32_e32 v93, v93, v248
	v_sub_f32_e32 v94, v94, v248
	v_sub_f32_e32 v95, v95, v248
	v_add_f32_e32 v188, v188, v248
	v_mul_f32_e32 v189, v189, v250
	v_pk_mul_f32 v[0:1], v[0:1], v[250:251] op_sel_hi:[1,0]
	v_pk_mul_f32 v[2:3], v[2:3], v[250:251] op_sel_hi:[1,0]
	v_pk_mul_f32 v[4:5], v[4:5], v[250:251] op_sel_hi:[1,0]
	v_pk_mul_f32 v[6:7], v[6:7], v[250:251] op_sel_hi:[1,0]
	v_pk_mul_f32 v[8:9], v[8:9], v[250:251] op_sel_hi:[1,0]
	v_pk_mul_f32 v[10:11], v[10:11], v[250:251] op_sel_hi:[1,0]
	v_pk_mul_f32 v[12:13], v[12:13], v[250:251] op_sel_hi:[1,0]
	v_pk_mul_f32 v[14:15], v[14:15], v[250:251] op_sel_hi:[1,0]
	v_pk_mul_f32 v[16:17], v[16:17], v[250:251] op_sel_hi:[1,0]
	v_pk_mul_f32 v[18:19], v[18:19], v[250:251] op_sel_hi:[1,0]
	v_pk_mul_f32 v[20:21], v[20:21], v[250:251] op_sel_hi:[1,0]
	v_pk_mul_f32 v[22:23], v[22:23], v[250:251] op_sel_hi:[1,0]
	v_pk_mul_f32 v[24:25], v[24:25], v[250:251] op_sel_hi:[1,0]
	v_pk_mul_f32 v[26:27], v[26:27], v[250:251] op_sel_hi:[1,0]
	v_pk_mul_f32 v[28:29], v[28:29], v[250:251] op_sel_hi:[1,0]
	v_pk_mul_f32 v[30:31], v[30:31], v[250:251] op_sel_hi:[1,0]
	v_pk_mul_f32 v[32:33], v[32:33], v[250:251] op_sel_hi:[1,0]
	v_pk_mul_f32 v[34:35], v[34:35], v[250:251] op_sel_hi:[1,0]
	v_pk_mul_f32 v[36:37], v[36:37], v[250:251] op_sel_hi:[1,0]
	v_pk_mul_f32 v[38:39], v[38:39], v[250:251] op_sel_hi:[1,0]
	v_pk_mul_f32 v[40:41], v[40:41], v[250:251] op_sel_hi:[1,0]
	v_pk_mul_f32 v[42:43], v[42:43], v[250:251] op_sel_hi:[1,0]
	v_pk_mul_f32 v[44:45], v[44:45], v[250:251] op_sel_hi:[1,0]
	v_pk_mul_f32 v[46:47], v[46:47], v[250:251] op_sel_hi:[1,0]
	v_pk_mul_f32 v[48:49], v[48:49], v[250:251] op_sel_hi:[1,0]
	v_pk_mul_f32 v[50:51], v[50:51], v[250:251] op_sel_hi:[1,0]
	v_pk_mul_f32 v[52:53], v[52:53], v[250:251] op_sel_hi:[1,0]
	v_pk_mul_f32 v[54:55], v[54:55], v[250:251] op_sel_hi:[1,0]
	v_pk_mul_f32 v[56:57], v[56:57], v[250:251] op_sel_hi:[1,0]
	v_pk_mul_f32 v[58:59], v[58:59], v[250:251] op_sel_hi:[1,0]
	v_pk_mul_f32 v[60:61], v[60:61], v[250:251] op_sel_hi:[1,0]
	v_pk_mul_f32 v[62:63], v[62:63], v[250:251] op_sel_hi:[1,0]
	v_sub_f32_e32 v96, 0, v188
	v_mov_b32_e32 v97, v96
	v_mov_b32_e32 v98, v96
	v_mov_b32_e32 v99, v96
	v_mov_b32_e32 v100, v96
	v_mov_b32_e32 v101, v96
	v_mov_b32_e32 v102, v96
	v_mov_b32_e32 v103, v96
	v_mov_b32_e32 v104, v96
	v_mov_b32_e32 v105, v96
	v_mov_b32_e32 v106, v96
	v_mov_b32_e32 v107, v96
	v_mov_b32_e32 v108, v96
	v_mov_b32_e32 v109, v96
	v_mov_b32_e32 v110, v96
	v_mov_b32_e32 v111, v96
	s_branch .Latt_cont_a
